# transposes wait only for attention-unit completion (KN dead) instead of whole queue
# speedup vs baseline: 1.0049x; 1.0029x over previous
.LBB0_525:
	s_or_b64 exec, exec, s[6:7]
	s_waitcnt lgkmcnt(0)
	s_barrier
	s_waitcnt vmcnt(16)
	ds_read_b32 v0, v110
	s_mov_b64 s[6:7], -1
	s_waitcnt lgkmcnt(0)
	v_cmp_lt_i32_e32 vcc, s59, v0
	v_readfirstlane_b32 s52, v0
	s_cbranch_vccnz .LBB0_520
	s_cmpk_gt_i32 s52, 0x1ff
	s_cselect_b32 s99, 0, 1
	s_cbranch_scc0 .LBB0_536
	s_and_b32 s8, s52, 3
	v_cvt_f32_ubyte0_e32 v0, s8
	v_sub_f32_e32 v0, 0xc0a00000, v0
	v_cmp_gt_f32_e32 vcc, s60, v0
	s_bfe_u32 s9, s52, 0x20002
	s_and_b64 s[6:7], vcc, exec
	s_waitcnt vmcnt(15)
	v_cndmask_b32_e32 v1, 0, v111, vcc
	v_add_f32_e32 v0, v0, v1
	v_exp_f32_e32 v0, v0
	s_cselect_b32 s6, 0xffffffc0, 0
	v_mov_b32_e32 v36, v152
	v_ldexp_f32 v0, v0, s6
	s_waitcnt vmcnt(0)
	v_sub_f32_e32 v16, 1.0, v0
	v_cmp_gt_f32_e32 vcc, s61, v16
	s_and_b64 s[6:7], vcc, exec
	s_cselect_b32 s11, 32, 0
	s_lshl_b32 s6, s52, 4
	s_and_b32 s10, s6, 0x7fffff00
	v_ashrrev_i32_e32 v0, 1, v36
	s_addk_i32 s10, 0xe000
	v_and_b32_e32 v80, 0xffffffe0, v0
	v_and_b32_e32 v92, 31, v36
	v_add_u32_e32 v37, s10, v80
	v_or_b32_e32 v0, v37, v92
	s_lshl_b32 s14, s9, 12
	v_ashrrev_i32_e32 v1, 31, v0
	v_lshl_add_u64 v[8:9], v[0:1], 0, s[14:15]
	v_bfe_u32 v93, v36, 5, 1
	v_lshlrev_b64 v[0:1], 7, v[8:9]
	v_lshl_add_u64 v[2:3], s[20:21], 0, v[0:1]
	v_lshlrev_b32_e32 v4, 5, v93
	v_mov_b32_e32 v5, v101
	v_lshl_add_u64 v[0:1], s[22:23], 0, v[0:1]
	v_lshlrev_b64 v[8:9], 11, v[8:9]
	v_lshl_add_u64 v[28:29], v[0:1], 0, v[4:5]
	v_lshl_add_u64 v[8:9], s[34:35], 0, v[8:9]
	s_lshl_b32 s6, s8, 7
	s_mov_b32 s7, s15
	v_lshl_add_u64 v[26:27], v[2:3], 0, v[4:5]
	global_load_dwordx4 v[0:3], v[28:29], off
	global_load_dwordx4 v[4:7], v[26:27], off
	v_lshl_add_u64 v[8:9], v[8:9], 0, s[6:7]
	v_lshlrev_b32_e32 v100, 4, v93
	v_lshl_add_u64 v[30:31], v[8:9], 0, v[100:101]
	global_load_dwordx4 v[8:11], v[30:31], off
	global_load_dwordx4 v[12:15], v[30:31], off offset:64
	global_load_dwordx4 v[18:21], v[28:29], off offset:16
	global_load_dwordx4 v[22:25], v[26:27], off offset:16
	v_ldexp_f32 v16, v16, s11
	v_log_f32_e32 v16, v16
	v_bitop3_b32 v32, v37, s62, v92 bitop3:0xc8
	v_cndmask_b32_e32 v17, 0, v112, vcc
	v_add_u32_e32 v32, 1, v32
	v_sub_f32_e32 v81, v16, v17
	v_cvt_f32_ubyte0_e32 v16, v32
	v_mul_f32_e32 v17, v81, v16
	v_cmp_gt_f32_e32 vcc, s60, v17
	s_lshl_b32 s7, s9, 7
	s_lshl_b32 s9, s8, 5
	v_cndmask_b32_e32 v17, 0, v111, vcc
	v_fmac_f32_e32 v17, v81, v16
	v_exp_f32_e32 v16, v17
	v_cndmask_b32_e32 v17, 0, v113, vcc
	v_ashrrev_i32_e32 v94, 7, v37
	s_or_b32 s7, s7, s9
	v_ldexp_f32 v46, v16, v17
	s_lshl_b32 s11, s8, 6
	s_add_u32 s6, s34, s6
	v_or_b32_e32 v96, 31, v37
	v_mul_u32_u24_e32 v37, 0x68, v92
	s_mov_b32 s53, 0
	s_mov_b32 s54, s10
	s_waitcnt vmcnt(5)
	v_mov_b32_e32 v16, v0
	v_mov_b32_e32 v33, v0
	s_waitcnt vmcnt(4)
	v_mov_b32_e32 v0, v5
	s_waitcnt vmcnt(3)
	v_and_b32_e32 v43, 0xffff0000, v8
	s_waitcnt vmcnt(2)
	v_and_b32_e32 v42, 0xffff0000, v12
	v_mov_b32_e32 v17, v4
	v_mov_b32_e32 v32, v4
	v_mov_b32_e32 v4, v1
	v_mov_b32_e32 v34, v2
	v_mov_b32_e32 v35, v6
	v_mov_b32_e32 v38, v6
	v_mov_b32_e32 v6, v3
	v_lshlrev_b32_e32 v41, 16, v8
	v_lshlrev_b32_e32 v40, 16, v12
	v_lshlrev_b32_e32 v45, 16, v9
	v_lshlrev_b32_e32 v44, 16, v13
	v_and_b32_e32 v9, 0xffff0000, v9
	v_and_b32_e32 v8, 0xffff0000, v13
	v_pk_mul_f32 v[0:1], v[0:1], v[42:43]
	v_mov_b32_e32 v39, v2
	v_mov_b32_e32 v2, v7
	v_pk_mul_f32 v[12:13], v[16:17], v[40:41]
	v_pk_mul_f32 v[16:17], v[32:33], v[40:41]
	v_pk_mul_f32 v[4:5], v[4:5], v[42:43]
	v_pk_mul_f32 v[32:33], v[34:35], v[44:45]
	v_pk_mul_f32 v[6:7], v[6:7], v[8:9]
	v_add_f32_e32 v0, v0, v1
	v_pk_mul_f32 v[34:35], v[38:39], v[44:45]
	v_pk_mul_f32 v[2:3], v[2:3], v[8:9]
	v_sub_f32_e32 v8, v13, v12
	v_add_f32_e32 v9, v16, v17
	v_sub_f32_e32 v4, v5, v4
	v_sub_f32_e32 v1, v33, v32
	v_sub_f32_e32 v6, v7, v6
	v_cvt_pk_bf16_f32 v64, v8, v4
	v_cvt_pk_bf16_f32 v68, v9, v0
	v_mul_f32_e32 v0, v0, v46
	v_add_f32_e32 v5, v34, v35
	v_add_f32_e32 v2, v2, v3
	v_mul_f32_e32 v3, v8, v46
	v_mul_f32_e32 v4, v4, v46
	v_mul_f32_e32 v7, v9, v46
	v_cvt_pk_bf16_f32 v16, v3, v4
	v_cvt_pk_bf16_f32 v32, v7, v0
	v_cvt_pk_bf16_f32 v65, v1, v6
	v_mul_f32_e32 v0, v1, v46
	v_mul_f32_e32 v1, v6, v46
	v_cvt_pk_bf16_f32 v69, v5, v2
	v_cvt_pk_bf16_f32 v17, v0, v1
	v_mul_f32_e32 v0, v5, v46
	v_mul_f32_e32 v1, v2, v46
	v_cvt_pk_bf16_f32 v33, v0, v1
	v_lshlrev_b32_e32 v1, 16, v10
	v_lshlrev_b32_e32 v0, 16, v14
	s_waitcnt vmcnt(1)
	v_mov_b32_e32 v2, v18
	s_waitcnt vmcnt(0)
	v_mov_b32_e32 v3, v22
	v_pk_mul_f32 v[2:3], v[2:3], v[0:1]
	s_nop 0
	v_sub_f32_e32 v4, v3, v2
	v_mov_b32_e32 v2, v22
	v_mov_b32_e32 v3, v18
	v_pk_mul_f32 v[0:1], v[2:3], v[0:1]
	v_mov_b32_e32 v22, v19
	v_add_f32_e32 v5, v0, v1
	v_and_b32_e32 v1, 0xffff0000, v10
	v_and_b32_e32 v0, 0xffff0000, v14
	v_mov_b32_e32 v18, v23
	v_pk_mul_f32 v[2:3], v[22:23], v[0:1]
	v_pk_mul_f32 v[0:1], v[18:19], v[0:1]
	v_sub_f32_e32 v2, v3, v2
	v_add_f32_e32 v0, v0, v1
	v_mul_f32_e32 v1, v46, v4
	v_cvt_pk_bf16_f32 v66, v4, v2
	v_cvt_pk_bf16_f32 v70, v5, v0
	v_mul_f32_e32 v2, v46, v2
	v_cvt_pk_bf16_f32 v18, v1, v2
	v_mul_f32_e32 v1, v46, v5
	v_mul_f32_e32 v0, v46, v0
	v_cvt_pk_bf16_f32 v34, v1, v0
	v_lshlrev_b32_e32 v1, 16, v11
	v_lshlrev_b32_e32 v0, 16, v15
	v_mov_b32_e32 v2, v20
	v_mov_b32_e32 v3, v24
	v_pk_mul_f32 v[2:3], v[2:3], v[0:1]
	s_nop 0
	v_sub_f32_e32 v4, v3, v2
	v_mov_b32_e32 v2, v24
	v_mov_b32_e32 v3, v20
	v_pk_mul_f32 v[0:1], v[2:3], v[0:1]
	v_mov_b32_e32 v24, v21
	v_add_f32_e32 v5, v0, v1
	v_and_b32_e32 v1, 0xffff0000, v11
	v_and_b32_e32 v0, 0xffff0000, v15
	v_mov_b32_e32 v20, v25
	v_pk_mul_f32 v[2:3], v[24:25], v[0:1]
	v_pk_mul_f32 v[0:1], v[20:21], v[0:1]
	v_sub_f32_e32 v2, v3, v2
	v_add_f32_e32 v0, v0, v1
	v_mul_f32_e32 v1, v46, v4
	v_cvt_pk_bf16_f32 v67, v4, v2
	v_cvt_pk_bf16_f32 v71, v5, v0
	v_mul_f32_e32 v2, v46, v2
	v_cvt_pk_bf16_f32 v19, v1, v2
	v_mul_f32_e32 v1, v46, v5
	v_mul_f32_e32 v0, v46, v0
	v_cvt_pk_bf16_f32 v35, v1, v0
	global_load_dwordx4 v[0:3], v[30:31], off offset:32
	global_load_dwordx4 v[4:7], v[30:31], off offset:96
	global_load_dwordx4 v[8:11], v[28:29], off offset:64
	global_load_dwordx4 v[12:15], v[26:27], off offset:64
	global_load_dwordx4 v[20:23], v[28:29], off offset:80
	s_nop 0
	global_load_dwordx4 v[24:27], v[26:27], off offset:80
	s_waitcnt vmcnt(5)
	v_lshlrev_b32_e32 v29, 16, v0
	s_waitcnt vmcnt(4)
	v_lshlrev_b32_e32 v28, 16, v4
	s_waitcnt vmcnt(3)
	v_mov_b32_e32 v30, v8
	s_waitcnt vmcnt(2)
	v_mov_b32_e32 v31, v12
	v_mov_b32_e32 v38, v12
	v_and_b32_e32 v41, 0xffff0000, v0
	v_and_b32_e32 v40, 0xffff0000, v4
	v_mov_b32_e32 v12, v9
	v_mov_b32_e32 v39, v8
	v_mov_b32_e32 v8, v13
	v_pk_mul_f32 v[30:31], v[30:31], v[28:29]
	v_pk_mul_f32 v[12:13], v[12:13], v[40:41]
	v_pk_mul_f32 v[28:29], v[38:39], v[28:29]
	v_pk_mul_f32 v[8:9], v[8:9], v[40:41]
	v_sub_f32_e32 v0, v31, v30
	v_sub_f32_e32 v12, v13, v12
	v_add_f32_e32 v4, v28, v29
	v_add_f32_e32 v8, v8, v9
	v_cvt_pk_bf16_f32 v72, v0, v12
	v_mul_f32_e32 v0, v46, v0
	v_mul_f32_e32 v9, v46, v12
	v_cvt_pk_bf16_f32 v76, v4, v8
	v_cvt_pk_bf16_f32 v38, v0, v9
	v_mul_f32_e32 v0, v46, v4
	v_mul_f32_e32 v4, v46, v8
	v_lshlrev_b32_e32 v9, 16, v1
	v_lshlrev_b32_e32 v8, 16, v5
	v_mov_b32_e32 v12, v10
	v_mov_b32_e32 v13, v14
	v_pk_mul_f32 v[12:13], v[12:13], v[8:9]
	v_cvt_pk_bf16_f32 v42, v0, v4
	v_and_b32_e32 v1, 0xffff0000, v1
	v_sub_f32_e32 v28, v13, v12
	v_mov_b32_e32 v12, v14
	v_mov_b32_e32 v13, v10
	v_and_b32_e32 v0, 0xffff0000, v5
	v_mov_b32_e32 v14, v11
	v_mov_b32_e32 v10, v15
	v_pk_mul_f32 v[8:9], v[12:13], v[8:9]
	v_pk_mul_f32 v[4:5], v[14:15], v[0:1]
	v_pk_mul_f32 v[0:1], v[10:11], v[0:1]
	v_add_f32_e32 v8, v8, v9
	v_sub_f32_e32 v4, v5, v4
	v_add_f32_e32 v0, v0, v1
	v_mul_f32_e32 v1, v46, v28
	v_cvt_pk_bf16_f32 v73, v28, v4
	v_cvt_pk_bf16_f32 v77, v8, v0
	v_mul_f32_e32 v4, v46, v4
	v_cvt_pk_bf16_f32 v39, v1, v4
	v_mul_f32_e32 v1, v46, v8
	v_mul_f32_e32 v0, v46, v0
	v_cvt_pk_bf16_f32 v43, v1, v0
	v_lshlrev_b32_e32 v1, 16, v2
	v_lshlrev_b32_e32 v0, 16, v6
	s_waitcnt vmcnt(1)
	v_mov_b32_e32 v4, v20
	s_waitcnt vmcnt(0)
	v_mov_b32_e32 v5, v24
	v_pk_mul_f32 v[4:5], v[4:5], v[0:1]
	s_nop 0
	v_sub_f32_e32 v8, v5, v4
	v_mov_b32_e32 v4, v24
	v_mov_b32_e32 v5, v20
	v_pk_mul_f32 v[0:1], v[4:5], v[0:1]
	v_mov_b32_e32 v24, v21
	v_add_f32_e32 v9, v0, v1
	v_and_b32_e32 v1, 0xffff0000, v2
	v_and_b32_e32 v0, 0xffff0000, v6
	v_mov_b32_e32 v20, v25
	v_pk_mul_f32 v[4:5], v[24:25], v[0:1]
	v_pk_mul_f32 v[0:1], v[20:21], v[0:1]
	v_sub_f32_e32 v2, v5, v4
	v_add_f32_e32 v0, v0, v1
	v_mul_f32_e32 v1, v46, v8
	v_cvt_pk_bf16_f32 v74, v8, v2
	v_cvt_pk_bf16_f32 v78, v9, v0
	v_mul_f32_e32 v2, v46, v2
	v_cvt_pk_bf16_f32 v40, v1, v2
	v_mul_f32_e32 v1, v46, v9
	v_mul_f32_e32 v0, v46, v0
	v_cvt_pk_bf16_f32 v44, v1, v0
	v_lshlrev_b32_e32 v1, 16, v3
	v_lshlrev_b32_e32 v0, 16, v7
	v_mov_b32_e32 v4, v22
	v_mov_b32_e32 v5, v26
	v_pk_mul_f32 v[4:5], v[4:5], v[0:1]
	s_nop 0
	v_sub_f32_e32 v6, v5, v4
	v_mov_b32_e32 v4, v26
	v_mov_b32_e32 v5, v22
	v_pk_mul_f32 v[0:1], v[4:5], v[0:1]
	v_mov_b32_e32 v26, v23
	v_add_f32_e32 v4, v0, v1
	v_and_b32_e32 v1, 0xffff0000, v3
	v_and_b32_e32 v0, 0xffff0000, v7
	v_mov_b32_e32 v22, v27
	v_pk_mul_f32 v[2:3], v[26:27], v[0:1]
	v_pk_mul_f32 v[0:1], v[22:23], v[0:1]
	v_sub_f32_e32 v2, v3, v2
	v_add_f32_e32 v0, v0, v1
	v_cvt_pk_bf16_f32 v75, v6, v2
	v_cvt_pk_bf16_f32 v79, v4, v0
	v_mul_f32_e32 v1, v46, v6
	v_mul_f32_e32 v0, v46, v0
	v_mul_f32_e32 v2, v46, v2
	v_cvt_pk_bf16_f32 v41, v1, v2
	v_mul_f32_e32 v1, v46, v4
	v_cvt_pk_bf16_f32 v45, v1, v0
	v_add_u32_e32 v0, s7, v94
	v_ashrrev_i32_e32 v1, 31, v0
	v_lshlrev_b64 v[0:1], 13, v[0:1]
	v_lshl_add_u64 v[0:1], s[36:37], 0, v[0:1]
	v_lshlrev_b32_e32 v2, 7, v92
	v_mov_b32_e32 v3, v101
	v_lshl_add_u64 v[0:1], v[0:1], 0, v[2:3]
	v_lshl_add_u64 v[62:63], v[0:1], 0, v[100:101]
	global_load_dwordx4 v[0:3], v[62:63], off
	v_add_co_u32_e32 v4, vcc, s63, v62
	v_lshl_add_u64 v[82:83], v[62:63], 0, s[48:49]
	s_nop 0
	v_addc_co_u32_e32 v5, vcc, 0, v63, vcc
	global_load_dwordx4 v[20:23], v[4:5], off
	global_load_dwordx4 v[46:49], v[62:63], off offset:32
	global_load_dwordx4 v[50:53], v[82:83], off offset:32
	global_load_dwordx4 v[54:57], v[82:83], off offset:96
	s_waitcnt vmcnt(4)
	v_mfma_f32_32x32x16_bf16 v[0:15], v[16:19], v[0:3], 0
	global_load_dwordx4 v[58:61], v[62:63], off offset:64
	s_addc_u32 s7, s35, 0
	v_cmp_lt_i32_e32 vcc, s64, v36
	s_waitcnt vmcnt(4)
	v_mfma_f32_32x32x16_bf16 v[16:31], v[16:19], v[20:23], 0
	s_waitcnt vmcnt(3)
	v_mfma_f32_32x32x16_bf16 v[0:15], v[38:41], v[46:49], v[0:15]
	global_load_dwordx4 v[46:49], v[82:83], off offset:64
	s_waitcnt vmcnt(3)
	v_mfma_f32_32x32x16_bf16 v[16:31], v[38:41], v[50:53], v[16:31]
	global_load_dwordx4 v[38:41], v[62:63], off offset:96
	s_waitcnt vmcnt(2)
	v_mfma_f32_32x32x16_bf16 v[0:15], v[32:35], v[58:61], v[0:15]
	s_waitcnt vmcnt(1)
	v_mfma_f32_32x32x16_bf16 v[16:31], v[32:35], v[46:49], v[16:31]
	v_bfe_u32 v35, v36, 2, 6
	v_mov_b32_e32 v33, v101
	v_lshlrev_b32_e32 v34, 3, v93
	v_or_b32_e32 v98, s14, v35
	s_waitcnt vmcnt(0)
	v_mfma_f32_32x32x16_bf16 v[0:15], v[42:45], v[38:41], v[0:15]
	v_and_b32_e32 v38, 3, v36
	v_lshlrev_b32_e32 v100, 4, v38
	v_lshlrev_b32_e32 v39, 3, v38
	v_lshlrev_b32_e32 v32, 5, v38
	v_mul_u32_u24_e32 v40, 0x68, v35
	v_add_lshl_u32 v95, v40, v39, 1
	v_lshl_add_u64 v[86:87], s[6:7], 0, v[32:33]
	v_mfma_f32_32x32x16_bf16 v[16:31], v[42:45], v[54:57], v[16:31]
	v_lshl_add_u64 v[88:89], s[6:7], 0, v[100:101]
	s_add_i32 s6, s10, s14
	v_lshl_add_u32 v36, v35, 1, 0
	v_lshl_add_u64 v[82:83], s[20:21], 0, v[32:33]
	v_lshl_add_u64 v[84:85], s[22:23], 0, v[32:33]
	v_add_u32_e32 v39, 64, v95
	v_mul_i32_i24_e32 v40, -4, v93
	v_add_u32_e32 v41, 0, v34
	v_mul_u32_u24_e32 v38, 0x900, v38
	v_add_lshl_u32 v34, v34, v37, 1
	v_mul_u32_u24_e32 v37, 0x90, v92
	v_or_b32_e32 v32, s6, v35
	v_add3_u32 v97, v40, v80, v92
	v_lshlrev_b32_e32 v90, 10, v32
	v_add_u32_e32 v99, v36, v38
	v_add_u32_e32 v102, 0, v39
	v_add_u32_e32 v103, 0, v34
	v_add_u32_e32 v104, v41, v37
	s_branch .LBB0_529

.Lxp0_wloop:
	global_load_dword v0, v101, s[16:17] offset:768 sc1
	s_waitcnt vmcnt(0)
	v_cmp_gt_u32_e32 vcc, 0x200, v0
	s_cbranch_vccz .Lxp0_wdone
	s_sub_u32 s98, s98, 1
	s_cmp_eq_u32 s98, 0
	s_cbranch_scc1 .Lxp0_wdone
	s_sleep 8
	s_branch .Lxp0_wloop

.Lxp1_wloop:
	global_load_dword v0, v101, s[16:17] offset:1024 sc1
	s_waitcnt vmcnt(0)
	v_cmp_gt_u32_e32 vcc, 0x200, v0
	s_cbranch_vccz .Lxp1_wdone
	s_sub_u32 s98, s98, 1
	s_cmp_eq_u32 s98, 0
	s_cbranch_scc1 .Lxp1_wdone
	s_sleep 8
	s_branch .Lxp1_wloop
